# combo1 + hand-written SwiGLU GEMM epilogue (permlane butterfly for the row rstd, fewer VALU)
# speedup vs baseline: 1.0033x; 1.0033x over previous
; __device__ __forceinline__ unsigned cvtpk(float lo, float hi) { f32x2 v = {lo, hi}; bf16x2_t b = __builtin_convertvector(v, bf16x2_t); return __builtin_bit_cast(unsigned, b); }
; __device__ __forceinline__ void load_rstd(const float* ssq, int row0, int fq, float (&rs)[2][4]) {
; #pragma unroll
;     for (int ai = 0; ai < 2; ++ai)
; #pragma unroll
;         for (int m = 0; m < 4; ++m) {
;             const f32x4 v = *(const f32x4*)(ssq + (size_t)(row0 + ai * HALF + m * 16) * 16 + 4 * fq);
;             float s = (v[0] + v[1]) + (v[2] + v[3]);
;             s += shx<16>(s); s += shx<32>(s);
;             rs[ai][m] = rsqrtf(s * (1.0f / 1024.0f) + RMS_EPS_F);
;         }
; }
;     __device__ __forceinline__ void operator()(const f32x4 (&acc)[2][2][4][2], const Unit& u, int wr, int wc, int fr, int fq) const {
;         const int row0 = u.pm * BM + wr * 64 + fr;
;         const int col0 = 128 * u.pn + 32 * wc + 8 * fq;
;         float rs[2][4]; load_rstd(ssq, row0, fq, rs);
; #pragma unroll
;         for (int ai = 0; ai < 2; ++ai)
; #pragma unroll
;             for (int m = 0; m < 4; ++m) {
;                 const float mul = rs[ai][m], nml = -mul * LOG2E_F, mul2 = mul * mul;
;                 float hv[8];
; #pragma unroll
;                 for (int n = 0; n < 2; ++n)
; #pragma unroll
;                     for (int i = 0; i < 4; ++i) {
;                         const float ag = acc[ai][0][m][n][i];
;                         const float e = __builtin_amdgcn_exp2f(ag * nml);
;                         hv[4 * n + i] = (ag * acc[ai][1][m][n][i]) * (mul2 * __builtin_amdgcn_rcpf(1.0f + e));
;                     }
;                 u32x4 w; w.x = cvtpk(hv[0], hv[1]); w.y = cvtpk(hv[2], hv[3]); w.z = cvtpk(hv[4], hv[5]); w.w = cvtpk(hv[6], hv[7]);
;                 *(u32x4*)(H + (size_t)(row0 + ai * HALF + m * 16) * 2816 + col0) = w;
.LBB0_408:
	v_lshl_add_u32 v144, s6, 8, v3
	v_lshlrev_b32_e32 v146, 6, v144
	v_mov_b32_e32 v147, v2
	v_lshl_add_u64 v[148:149], v[138:139], 0, v[146:147]
	s_mov_b32 s100, 0x2000
	s_mov_b32 s101, 0
	v_lshl_add_u64 v[150:151], v[148:149], 0, s[100:101]
	global_load_dwordx4 v[168:171], v[148:149], off
	global_load_dwordx4 v[172:175], v[148:149], off offset:1024
	global_load_dwordx4 v[176:179], v[148:149], off offset:2048
	global_load_dwordx4 v[180:183], v[148:149], off offset:3072
	global_load_dwordx4 v[184:187], v[150:151], off
	global_load_dwordx4 v[188:191], v[150:151], off offset:1024
	global_load_dwordx4 v[192:195], v[150:151], off offset:2048
	global_load_dwordx4 v[202:205], v[150:151], off offset:3072
	v_mov_b64_e32 v[146:147], s[12:13]
	v_lshl_or_b32 v145, s3, 7, v165
	v_mad_i64_i32 v[226:227], s[6:7], v144, s88, v[146:147]
	v_lshlrev_b32_e32 v228, 1, v145
	v_mov_b32_e32 v229, v2
	v_lshl_add_u64 v[226:227], v[226:227], 0, v[228:229]
	v_mov_b32_e32 v147, 0x358637bd
	v_pk_mul_f32 v[124:125], v[128:129], v[124:125]
	v_pk_mul_f32 v[126:127], v[130:131], v[126:127]
	v_pk_mul_f32 v[116:117], v[120:121], v[116:117]
	v_pk_mul_f32 v[118:119], v[122:123], v[118:119]
	v_pk_mul_f32 v[108:109], v[112:113], v[108:109]
	v_pk_mul_f32 v[110:111], v[114:115], v[110:111]
	v_pk_mul_f32 v[100:101], v[104:105], v[100:101]
	v_pk_mul_f32 v[102:103], v[106:107], v[102:103]
	v_pk_mul_f32 v[92:93], v[96:97], v[92:93]
	v_pk_mul_f32 v[94:95], v[98:99], v[94:95]
	v_pk_mul_f32 v[84:85], v[88:89], v[84:85]
	v_pk_mul_f32 v[86:87], v[90:91], v[86:87]
	v_pk_mul_f32 v[76:77], v[80:81], v[76:77]
	v_pk_mul_f32 v[78:79], v[82:83], v[78:79]
	v_pk_mul_f32 v[68:69], v[72:73], v[68:69]
	v_pk_mul_f32 v[70:71], v[74:75], v[70:71]
	v_pk_mul_f32 v[60:61], v[64:65], v[60:61]
	v_pk_mul_f32 v[62:63], v[66:67], v[62:63]
	v_pk_mul_f32 v[52:53], v[56:57], v[52:53]
	v_pk_mul_f32 v[54:55], v[58:59], v[54:55]
	v_pk_mul_f32 v[44:45], v[48:49], v[44:45]
	v_pk_mul_f32 v[46:47], v[50:51], v[46:47]
	v_pk_mul_f32 v[36:37], v[40:41], v[36:37]
	v_pk_mul_f32 v[38:39], v[42:43], v[38:39]
	v_pk_mul_f32 v[28:29], v[32:33], v[28:29]
	v_pk_mul_f32 v[30:31], v[34:35], v[30:31]
	v_pk_mul_f32 v[20:21], v[24:25], v[20:21]
	v_pk_mul_f32 v[22:23], v[26:27], v[22:23]
	v_pk_mul_f32 v[12:13], v[16:17], v[12:13]
	v_pk_mul_f32 v[14:15], v[18:19], v[14:15]
	v_pk_mul_f32 v[4:5], v[8:9], v[4:5]
	v_pk_mul_f32 v[6:7], v[10:11], v[6:7]
	s_waitcnt vmcnt(7)
	v_add_f32_e32 v152, v168, v169
	v_add_f32_e32 v170, v170, v171
	v_add_f32_e32 v152, v152, v170
	s_waitcnt vmcnt(6)
	v_add_f32_e32 v153, v172, v173
	v_add_f32_e32 v174, v174, v175
	v_add_f32_e32 v153, v153, v174
	s_waitcnt vmcnt(5)
	v_add_f32_e32 v154, v176, v177
	v_add_f32_e32 v178, v178, v179
	v_add_f32_e32 v154, v154, v178
	s_waitcnt vmcnt(4)
	v_add_f32_e32 v155, v180, v181
	v_add_f32_e32 v182, v182, v183
	v_add_f32_e32 v155, v155, v182
	s_waitcnt vmcnt(3)
	v_add_f32_e32 v156, v184, v185
	v_add_f32_e32 v186, v186, v187
	v_add_f32_e32 v156, v156, v186
	s_waitcnt vmcnt(2)
	v_add_f32_e32 v157, v188, v189
	v_add_f32_e32 v190, v190, v191
	v_add_f32_e32 v157, v157, v190
	s_waitcnt vmcnt(1)
	v_add_f32_e32 v158, v192, v193
	v_add_f32_e32 v194, v194, v195
	v_add_f32_e32 v158, v158, v194
	s_waitcnt vmcnt(0)
	v_add_f32_e32 v159, v202, v203
	v_add_f32_e32 v204, v204, v205
	v_add_f32_e32 v159, v159, v204
	s_nop 1
	v_permlane32_swap_b32_e32 v152, v153
	v_permlane32_swap_b32_e32 v154, v155
	v_permlane32_swap_b32_e32 v156, v157
	v_permlane32_swap_b32_e32 v158, v159
	v_add_f32_e32 v152, v152, v153
	v_add_f32_e32 v154, v154, v155
	v_add_f32_e32 v156, v156, v157
	v_add_f32_e32 v158, v158, v159
	s_nop 1
	v_permlane16_swap_b32_e32 v152, v154
	v_permlane16_swap_b32_e32 v156, v158
	v_add_f32_e32 v152, v152, v154
	v_add_f32_e32 v156, v156, v158
	v_fmamk_f32 v160, v152, 0x3a800000, v147
	v_fmamk_f32 v161, v156, 0x3a800000, v147
	v_rsq_f32_e32 v162, v160
	v_rsq_f32_e32 v163, v161
	s_nop 0
	v_mul_f32_e32 v162, 0xbfb8aa3b, v162
	v_mul_f32_e32 v163, 0xbfb8aa3b, v163
	v_mov_b32_e32 v146, v160
	s_nop 1
	v_permlane16_swap_b32_e32 v160, v146
	v_mov_b32_e32 v202, v160
	v_mov_b32_e32 v204, v146
	v_mov_b32_e32 v203, v160
	v_mov_b32_e32 v205, v146
	s_nop 1
	v_permlane32_swap_b32_e32 v202, v203
	v_permlane32_swap_b32_e32 v204, v205
	v_mov_b32_e32 v146, v161
	s_nop 1
	v_permlane16_swap_b32_e32 v161, v146
	v_mov_b32_e32 v206, v161
	v_mov_b32_e32 v208, v146
	v_mov_b32_e32 v207, v161
	v_mov_b32_e32 v209, v146
	s_nop 1
	v_permlane32_swap_b32_e32 v206, v207
	v_permlane32_swap_b32_e32 v208, v209
	v_mov_b32_e32 v146, v162
	s_nop 1
	v_permlane16_swap_b32_e32 v162, v146
	v_mov_b32_e32 v210, v162
	v_mov_b32_e32 v212, v146
	v_mov_b32_e32 v211, v162
	v_mov_b32_e32 v213, v146
	s_nop 1
	v_permlane32_swap_b32_e32 v210, v211
	v_permlane32_swap_b32_e32 v212, v213
	v_mov_b32_e32 v146, v163
	s_nop 1
	v_permlane16_swap_b32_e32 v163, v146
	v_mov_b32_e32 v214, v163
	v_mov_b32_e32 v216, v146
	v_mov_b32_e32 v215, v163
	v_mov_b32_e32 v217, v146
	s_nop 1
	v_permlane32_swap_b32_e32 v214, v215
	v_permlane32_swap_b32_e32 v216, v217
	v_mul_f32_e32 v218, v128, v210
	v_mul_f32_e32 v219, v129, v210
	v_mul_f32_e32 v220, v130, v210
	v_mul_f32_e32 v221, v131, v210
	v_mul_f32_e32 v222, v120, v210
	v_mul_f32_e32 v223, v121, v210
	v_mul_f32_e32 v224, v122, v210
	v_mul_f32_e32 v225, v123, v210
	v_exp_f32_e32 v218, v218
	v_exp_f32_e32 v219, v219
	v_exp_f32_e32 v220, v220
	v_exp_f32_e32 v221, v221
	v_exp_f32_e32 v222, v222
	v_exp_f32_e32 v223, v223
	v_exp_f32_e32 v224, v224
	v_exp_f32_e32 v225, v225
	s_mov_b32 s100, 0x0
	v_lshl_add_u64 v[228:229], v[226:227], 0, s[100:101]
	v_fma_f32 v218, v218, v202, v202
	v_fma_f32 v219, v219, v202, v202
; __device__ __forceinline__ unsigned cvtpk(float lo, float hi) { f32x2 v = {lo, hi}; bf16x2_t b = __builtin_convertvector(v, bf16x2_t); return __builtin_bit_cast(unsigned, b); }
;     __device__ __forceinline__ void operator()(const f32x4 (&acc)[2][2][4][2], const Unit& u, int wr, int wc, int fr, int fq) const {
;     ...
;             for (int m = 0; m < 4; ++m) {
;                 const float mul = rs[ai][m], nml = -mul * LOG2E_F, mul2 = mul * mul;
;                 float hv[8];
; #pragma unroll
;                 for (int n = 0; n < 2; ++n)
; #pragma unroll
;                     for (int i = 0; i < 4; ++i) {
;                         const float ag = acc[ai][0][m][n][i];
;                         const float e = __builtin_amdgcn_exp2f(ag * nml);
;                         hv[4 * n + i] = (ag * acc[ai][1][m][n][i]) * (mul2 * __builtin_amdgcn_rcpf(1.0f + e));
;                     }
;                 u32x4 w; w.x = cvtpk(hv[0], hv[1]); w.y = cvtpk(hv[2], hv[3]); w.z = cvtpk(hv[4], hv[5]); w.w = cvtpk(hv[6], hv[7]);
;                 *(u32x4*)(H + (size_t)(row0 + ai * HALF + m * 16) * 2816 + col0) = w;
	v_fma_f32 v220, v220, v202, v202
	v_fma_f32 v221, v221, v202, v202
	v_fma_f32 v222, v222, v202, v202
	v_fma_f32 v223, v223, v202, v202
	v_fma_f32 v224, v224, v202, v202
	v_fma_f32 v225, v225, v202, v202
	v_rcp_f32_e32 v218, v218
	v_rcp_f32_e32 v219, v219
	v_rcp_f32_e32 v220, v220
	v_rcp_f32_e32 v221, v221
	v_rcp_f32_e32 v222, v222
	v_rcp_f32_e32 v223, v223
	v_rcp_f32_e32 v224, v224
	v_rcp_f32_e32 v225, v225
	s_nop 0
	v_pk_mul_f32 v[124:125], v[124:125], v[218:219]
	v_pk_mul_f32 v[126:127], v[126:127], v[220:221]
	v_pk_mul_f32 v[116:117], v[116:117], v[222:223]
	v_pk_mul_f32 v[118:119], v[118:119], v[224:225]
	v_cvt_pk_bf16_f32 v120, v124, v125
	v_cvt_pk_bf16_f32 v121, v126, v127
	v_cvt_pk_bf16_f32 v122, v116, v117
	v_cvt_pk_bf16_f32 v123, v118, v119
	global_store_dwordx4 v[228:229], v[120:123], off
	v_mul_f32_e32 v218, v112, v211
	v_mul_f32_e32 v219, v113, v211
	v_mul_f32_e32 v220, v114, v211
	v_mul_f32_e32 v221, v115, v211
	v_mul_f32_e32 v222, v104, v211
	v_mul_f32_e32 v223, v105, v211
	v_mul_f32_e32 v224, v106, v211
	v_mul_f32_e32 v225, v107, v211
	v_exp_f32_e32 v218, v218
	v_exp_f32_e32 v219, v219
	v_exp_f32_e32 v220, v220
	v_exp_f32_e32 v221, v221
	v_exp_f32_e32 v222, v222
	v_exp_f32_e32 v223, v223
	v_exp_f32_e32 v224, v224
	v_exp_f32_e32 v225, v225
	s_mov_b32 s100, 0x16000
	v_lshl_add_u64 v[228:229], v[226:227], 0, s[100:101]
	v_fma_f32 v218, v218, v203, v203
	v_fma_f32 v219, v219, v203, v203
	v_fma_f32 v220, v220, v203, v203
	v_fma_f32 v221, v221, v203, v203
	v_fma_f32 v222, v222, v203, v203
	v_fma_f32 v223, v223, v203, v203
	v_fma_f32 v224, v224, v203, v203
	v_fma_f32 v225, v225, v203, v203
	v_rcp_f32_e32 v218, v218
	v_rcp_f32_e32 v219, v219
	v_rcp_f32_e32 v220, v220
	v_rcp_f32_e32 v221, v221
	v_rcp_f32_e32 v222, v222
	v_rcp_f32_e32 v223, v223
	v_rcp_f32_e32 v224, v224
	v_rcp_f32_e32 v225, v225
	s_nop 0
	v_pk_mul_f32 v[108:109], v[108:109], v[218:219]
	v_pk_mul_f32 v[110:111], v[110:111], v[220:221]
	v_pk_mul_f32 v[100:101], v[100:101], v[222:223]
	v_pk_mul_f32 v[102:103], v[102:103], v[224:225]
	v_cvt_pk_bf16_f32 v104, v108, v109
	v_cvt_pk_bf16_f32 v105, v110, v111
	v_cvt_pk_bf16_f32 v106, v100, v101
	v_cvt_pk_bf16_f32 v107, v102, v103
	global_store_dwordx4 v[228:229], v[104:107], off
	v_mul_f32_e32 v218, v96, v212
	v_mul_f32_e32 v219, v97, v212
	v_mul_f32_e32 v220, v98, v212
	v_mul_f32_e32 v221, v99, v212
	v_mul_f32_e32 v222, v88, v212
	v_mul_f32_e32 v223, v89, v212
	v_mul_f32_e32 v224, v90, v212
	v_mul_f32_e32 v225, v91, v212
	v_exp_f32_e32 v218, v218
	v_exp_f32_e32 v219, v219
	v_exp_f32_e32 v220, v220
	v_exp_f32_e32 v221, v221
	v_exp_f32_e32 v222, v222
	v_exp_f32_e32 v223, v223
	v_exp_f32_e32 v224, v224
	v_exp_f32_e32 v225, v225
	s_mov_b32 s100, 0x2c000
	v_lshl_add_u64 v[228:229], v[226:227], 0, s[100:101]
	v_fma_f32 v218, v218, v204, v204
	v_fma_f32 v219, v219, v204, v204
	v_fma_f32 v220, v220, v204, v204
	v_fma_f32 v221, v221, v204, v204
	v_fma_f32 v222, v222, v204, v204
	v_fma_f32 v223, v223, v204, v204
	v_fma_f32 v224, v224, v204, v204
	v_fma_f32 v225, v225, v204, v204
	v_rcp_f32_e32 v218, v218
	v_rcp_f32_e32 v219, v219
	v_rcp_f32_e32 v220, v220
	v_rcp_f32_e32 v221, v221
	v_rcp_f32_e32 v222, v222
	v_rcp_f32_e32 v223, v223
	v_rcp_f32_e32 v224, v224
	v_rcp_f32_e32 v225, v225
	s_nop 0
	v_pk_mul_f32 v[92:93], v[92:93], v[218:219]
	v_pk_mul_f32 v[94:95], v[94:95], v[220:221]
	v_pk_mul_f32 v[84:85], v[84:85], v[222:223]
	v_pk_mul_f32 v[86:87], v[86:87], v[224:225]
	v_cvt_pk_bf16_f32 v88, v92, v93
	v_cvt_pk_bf16_f32 v89, v94, v95
	v_cvt_pk_bf16_f32 v90, v84, v85
	v_cvt_pk_bf16_f32 v91, v86, v87
	global_store_dwordx4 v[228:229], v[88:91], off
	v_mul_f32_e32 v218, v80, v213
	v_mul_f32_e32 v219, v81, v213
	v_mul_f32_e32 v220, v82, v213
	v_mul_f32_e32 v221, v83, v213
	v_mul_f32_e32 v222, v72, v213
	v_mul_f32_e32 v223, v73, v213
	v_mul_f32_e32 v224, v74, v213
	v_mul_f32_e32 v225, v75, v213
	v_exp_f32_e32 v218, v218
	v_exp_f32_e32 v219, v219
	v_exp_f32_e32 v220, v220
	v_exp_f32_e32 v221, v221
	v_exp_f32_e32 v222, v222
	v_exp_f32_e32 v223, v223
	v_exp_f32_e32 v224, v224
	v_exp_f32_e32 v225, v225
	s_mov_b32 s100, 0x42000
	v_lshl_add_u64 v[228:229], v[226:227], 0, s[100:101]
	v_fma_f32 v218, v218, v205, v205
	v_fma_f32 v219, v219, v205, v205
	v_fma_f32 v220, v220, v205, v205
	v_fma_f32 v221, v221, v205, v205
	v_fma_f32 v222, v222, v205, v205
	v_fma_f32 v223, v223, v205, v205
	v_fma_f32 v224, v224, v205, v205
	v_fma_f32 v225, v225, v205, v205
	v_rcp_f32_e32 v218, v218
	v_rcp_f32_e32 v219, v219
	v_rcp_f32_e32 v220, v220
	v_rcp_f32_e32 v221, v221
	v_rcp_f32_e32 v222, v222
	v_rcp_f32_e32 v223, v223
	v_rcp_f32_e32 v224, v224
	v_rcp_f32_e32 v225, v225
	s_nop 0
	v_pk_mul_f32 v[76:77], v[76:77], v[218:219]
	v_pk_mul_f32 v[78:79], v[78:79], v[220:221]
	v_pk_mul_f32 v[68:69], v[68:69], v[222:223]
	v_pk_mul_f32 v[70:71], v[70:71], v[224:225]
	v_cvt_pk_bf16_f32 v72, v76, v77
	v_cvt_pk_bf16_f32 v73, v78, v79
	v_cvt_pk_bf16_f32 v74, v68, v69
	v_cvt_pk_bf16_f32 v75, v70, v71
	global_store_dwordx4 v[228:229], v[72:75], off
	v_mul_f32_e32 v218, v64, v214
	v_mul_f32_e32 v219, v65, v214
	v_mul_f32_e32 v220, v66, v214
	v_mul_f32_e32 v221, v67, v214
	v_mul_f32_e32 v222, v56, v214
	v_mul_f32_e32 v223, v57, v214
	v_mul_f32_e32 v224, v58, v214
	v_mul_f32_e32 v225, v59, v214
	v_exp_f32_e32 v218, v218
	v_exp_f32_e32 v219, v219
	v_exp_f32_e32 v220, v220
	v_exp_f32_e32 v221, v221
; __device__ __forceinline__ unsigned cvtpk(float lo, float hi) { f32x2 v = {lo, hi}; bf16x2_t b = __builtin_convertvector(v, bf16x2_t); return __builtin_bit_cast(unsigned, b); }
; #define PG8_BAR __builtin_amdgcn_s_barrier()
;     __device__ __forceinline__ void operator()(const f32x4 (&acc)[2][2][4][2], const Unit& u, int wr, int wc, int fr, int fq) const {
;     ...
;             for (int m = 0; m < 4; ++m) {
;                 const float mul = rs[ai][m], nml = -mul * LOG2E_F, mul2 = mul * mul;
;                 float hv[8];
; #pragma unroll
;                 for (int n = 0; n < 2; ++n)
; #pragma unroll
;                     for (int i = 0; i < 4; ++i) {
;                         const float ag = acc[ai][0][m][n][i];
;                         const float e = __builtin_amdgcn_exp2f(ag * nml);
;                         hv[4 * n + i] = (ag * acc[ai][1][m][n][i]) * (mul2 * __builtin_amdgcn_rcpf(1.0f + e));
;                     }
;                 u32x4 w; w.x = cvtpk(hv[0], hv[1]); w.y = cvtpk(hv[2], hv[3]); w.z = cvtpk(hv[4], hv[5]); w.w = cvtpk(hv[6], hv[7]);
;                 *(u32x4*)(H + (size_t)(row0 + ai * HALF + m * 16) * 2816 + col0) = w;
; template <class Epi, class Sched, bool ALIGN_EPI = false, bool SP2 = false>
; __device__ __forceinline__ void gemm_phase(PG8_LAS unsigned char* lds, const Gemm g, const Sched& S, const Epi& E) {
;     ...
;         if (!has_next) break;
; #pragma unroll
;         for (int a = 0; a < 2; ++a)
; #pragma unroll
;             for (int b = 0; b < 2; ++b)
; #pragma unroll
;                 for (int m = 0; m < 4; ++m)
; #pragma unroll
;                     for (int n = 0; n < 2; ++n) acc[a][b][m][n] = (f32x4){0.f, 0.f, 0.f, 0.f};
;         cur = nxt; cA = nA; cB = nB; ++ui;
;         if constexpr (ALIGN_EPI) { if (wr == 1) PG8_BAR; }
	v_exp_f32_e32 v222, v222
	v_exp_f32_e32 v223, v223
	v_exp_f32_e32 v224, v224
	v_exp_f32_e32 v225, v225
	s_mov_b32 s100, 0xb0000
	v_lshl_add_u64 v[228:229], v[226:227], 0, s[100:101]
	v_fma_f32 v218, v218, v206, v206
	v_fma_f32 v219, v219, v206, v206
	v_fma_f32 v220, v220, v206, v206
	v_fma_f32 v221, v221, v206, v206
	v_fma_f32 v222, v222, v206, v206
	v_fma_f32 v223, v223, v206, v206
	v_fma_f32 v224, v224, v206, v206
	v_fma_f32 v225, v225, v206, v206
	v_rcp_f32_e32 v218, v218
	v_rcp_f32_e32 v219, v219
	v_rcp_f32_e32 v220, v220
	v_rcp_f32_e32 v221, v221
	v_rcp_f32_e32 v222, v222
	v_rcp_f32_e32 v223, v223
	v_rcp_f32_e32 v224, v224
	v_rcp_f32_e32 v225, v225
	s_nop 0
	v_pk_mul_f32 v[60:61], v[60:61], v[218:219]
	v_pk_mul_f32 v[62:63], v[62:63], v[220:221]
	v_pk_mul_f32 v[52:53], v[52:53], v[222:223]
	v_pk_mul_f32 v[54:55], v[54:55], v[224:225]
	v_cvt_pk_bf16_f32 v56, v60, v61
	v_cvt_pk_bf16_f32 v57, v62, v63
	v_cvt_pk_bf16_f32 v58, v52, v53
	v_cvt_pk_bf16_f32 v59, v54, v55
	global_store_dwordx4 v[228:229], v[56:59], off
	v_mul_f32_e32 v218, v48, v215
	v_mul_f32_e32 v219, v49, v215
	v_mul_f32_e32 v220, v50, v215
	v_mul_f32_e32 v221, v51, v215
	v_mul_f32_e32 v222, v40, v215
	v_mul_f32_e32 v223, v41, v215
	v_mul_f32_e32 v224, v42, v215
	v_mul_f32_e32 v225, v43, v215
	v_exp_f32_e32 v218, v218
	v_exp_f32_e32 v219, v219
	v_exp_f32_e32 v220, v220
	v_exp_f32_e32 v221, v221
	v_exp_f32_e32 v222, v222
	v_exp_f32_e32 v223, v223
	v_exp_f32_e32 v224, v224
	v_exp_f32_e32 v225, v225
	s_mov_b32 s100, 0xc6000
	v_lshl_add_u64 v[228:229], v[226:227], 0, s[100:101]
	v_fma_f32 v218, v218, v207, v207
	v_fma_f32 v219, v219, v207, v207
	v_fma_f32 v220, v220, v207, v207
	v_fma_f32 v221, v221, v207, v207
	v_fma_f32 v222, v222, v207, v207
	v_fma_f32 v223, v223, v207, v207
	v_fma_f32 v224, v224, v207, v207
	v_fma_f32 v225, v225, v207, v207
	v_rcp_f32_e32 v218, v218
	v_rcp_f32_e32 v219, v219
	v_rcp_f32_e32 v220, v220
	v_rcp_f32_e32 v221, v221
	v_rcp_f32_e32 v222, v222
	v_rcp_f32_e32 v223, v223
	v_rcp_f32_e32 v224, v224
	v_rcp_f32_e32 v225, v225
	s_nop 0
	v_pk_mul_f32 v[44:45], v[44:45], v[218:219]
	v_pk_mul_f32 v[46:47], v[46:47], v[220:221]
	v_pk_mul_f32 v[36:37], v[36:37], v[222:223]
	v_pk_mul_f32 v[38:39], v[38:39], v[224:225]
	v_cvt_pk_bf16_f32 v40, v44, v45
	v_cvt_pk_bf16_f32 v41, v46, v47
	v_cvt_pk_bf16_f32 v42, v36, v37
	v_cvt_pk_bf16_f32 v43, v38, v39
	global_store_dwordx4 v[228:229], v[40:43], off
	v_mul_f32_e32 v218, v32, v216
	v_mul_f32_e32 v219, v33, v216
	v_mul_f32_e32 v220, v34, v216
	v_mul_f32_e32 v221, v35, v216
	v_mul_f32_e32 v222, v24, v216
	v_mul_f32_e32 v223, v25, v216
	v_mul_f32_e32 v224, v26, v216
	v_mul_f32_e32 v225, v27, v216
	v_exp_f32_e32 v218, v218
	v_exp_f32_e32 v219, v219
	v_exp_f32_e32 v220, v220
	v_exp_f32_e32 v221, v221
	v_exp_f32_e32 v222, v222
	v_exp_f32_e32 v223, v223
	v_exp_f32_e32 v224, v224
	v_exp_f32_e32 v225, v225
	s_mov_b32 s100, 0xdc000
	v_lshl_add_u64 v[228:229], v[226:227], 0, s[100:101]
	v_fma_f32 v218, v218, v208, v208
	v_fma_f32 v219, v219, v208, v208
	v_fma_f32 v220, v220, v208, v208
	v_fma_f32 v221, v221, v208, v208
	v_fma_f32 v222, v222, v208, v208
	v_fma_f32 v223, v223, v208, v208
	v_fma_f32 v224, v224, v208, v208
	v_fma_f32 v225, v225, v208, v208
	v_rcp_f32_e32 v218, v218
	v_rcp_f32_e32 v219, v219
	v_rcp_f32_e32 v220, v220
	v_rcp_f32_e32 v221, v221
	v_rcp_f32_e32 v222, v222
	v_rcp_f32_e32 v223, v223
	v_rcp_f32_e32 v224, v224
	v_rcp_f32_e32 v225, v225
	s_nop 0
	v_pk_mul_f32 v[28:29], v[28:29], v[218:219]
	v_pk_mul_f32 v[30:31], v[30:31], v[220:221]
	v_pk_mul_f32 v[20:21], v[20:21], v[222:223]
	v_pk_mul_f32 v[22:23], v[22:23], v[224:225]
	v_cvt_pk_bf16_f32 v24, v28, v29
	v_cvt_pk_bf16_f32 v25, v30, v31
	v_cvt_pk_bf16_f32 v26, v20, v21
	v_cvt_pk_bf16_f32 v27, v22, v23
	global_store_dwordx4 v[228:229], v[24:27], off
	v_mul_f32_e32 v218, v16, v217
	v_mul_f32_e32 v219, v17, v217
	v_mul_f32_e32 v220, v18, v217
	v_mul_f32_e32 v221, v19, v217
	v_mul_f32_e32 v222, v8, v217
	v_mul_f32_e32 v223, v9, v217
	v_mul_f32_e32 v224, v10, v217
	v_mul_f32_e32 v225, v11, v217
	v_exp_f32_e32 v218, v218
	v_exp_f32_e32 v219, v219
	v_exp_f32_e32 v220, v220
	v_exp_f32_e32 v221, v221
	v_exp_f32_e32 v222, v222
	v_exp_f32_e32 v223, v223
	v_exp_f32_e32 v224, v224
	v_exp_f32_e32 v225, v225
	s_mov_b32 s100, 0xf2000
	v_lshl_add_u64 v[228:229], v[226:227], 0, s[100:101]
	v_fma_f32 v218, v218, v209, v209
	v_fma_f32 v219, v219, v209, v209
	v_fma_f32 v220, v220, v209, v209
	v_fma_f32 v221, v221, v209, v209
	v_fma_f32 v222, v222, v209, v209
	v_fma_f32 v223, v223, v209, v209
	v_fma_f32 v224, v224, v209, v209
	v_fma_f32 v225, v225, v209, v209
	v_rcp_f32_e32 v218, v218
	v_rcp_f32_e32 v219, v219
	v_rcp_f32_e32 v220, v220
	v_rcp_f32_e32 v221, v221
	v_rcp_f32_e32 v222, v222
	v_rcp_f32_e32 v223, v223
	v_rcp_f32_e32 v224, v224
	v_rcp_f32_e32 v225, v225
	s_nop 0
	v_pk_mul_f32 v[12:13], v[12:13], v[218:219]
	v_pk_mul_f32 v[14:15], v[14:15], v[220:221]
	v_pk_mul_f32 v[4:5], v[4:5], v[222:223]
	v_pk_mul_f32 v[6:7], v[6:7], v[224:225]
	v_cvt_pk_bf16_f32 v8, v12, v13
	v_cvt_pk_bf16_f32 v9, v14, v15
	v_cvt_pk_bf16_f32 v10, v4, v5
	v_cvt_pk_bf16_f32 v11, v6, v7
	global_store_dwordx4 v[228:229], v[8:11], off
	s_andn2_b64 vcc, exec, s[4:5]
	s_mov_b64 s[4:5], -1
	s_cbranch_vccnz .LBB0_401
	s_andn2_b64 vcc, exec, s[10:11]
	s_cbranch_vccnz .LBB0_400
	s_barrier
	s_branch .LBB0_400
